# P7 K-loop: LDS-DMA loads use SADDR form (SGPR pointer + 32-bit lane offset), 16 VALU 64-bit address adds per iteration removed
# speedup vs baseline: 1.0019x; 1.0019x over previous
.Lk7_peel:
	s_add_u32 s30, s28, 0xfffc0080
	s_addc_u32 s31, s29, -1
	s_add_i32 s63, 0, 0x10000
	s_cmp_eq_u32 s62, 12
	s_cselect_b32 s35, s25, s31
	s_cselect_b32 s34, s58, s30
	v_add_u32_e32 v142, s63, v145
	s_cselect_b32 s31, s23, s61
	s_cselect_b32 s30, s59, s60
	s_add_i32 s66, 0, 0x14000
	ds_read_b128 v[148:151], v142
	ds_read_b128 v[152:155], v142 offset:1024
	ds_read_b128 v[156:159], v142 offset:2048
	ds_read_b128 v[160:163], v142 offset:3072
	v_add_u32_e32 v142, s66, v145
	ds_read_b128 v[164:167], v142
	ds_read_b128 v[168:171], v142 offset:1024
	ds_read_b128 v[172:175], v142 offset:2048
	ds_read_b128 v[176:179], v142 offset:3072
	s_add_i32 m0, s45, 0xc000
	ds_read_b128 v[180:183], v146
	ds_read_b128 v[184:187], v146 offset:1024
	ds_read_b128 v[188:191], v146 offset:2048
	ds_read_b128 v[192:195], v146 offset:3072
	ds_read_b128 v[206:209], v146 offset:4096
	ds_read_b128 v[210:213], v146 offset:5120
	ds_read_b128 v[214:217], v146 offset:6144
	ds_read_b128 v[218:221], v146 offset:7168
	global_load_lds_dwordx4 v138, s[28:29]
	s_add_i32 m0, s45, 0xe000
	s_nop 0
	global_load_lds_dwordx4 v140, s[28:29]
	s_waitcnt vmcnt(8)
	s_waitcnt lgkmcnt(0)
	s_barrier
	s_waitcnt lgkmcnt(0)
	v_mfma_f32_16x16x32_bf16 v[128:131], v[148:151], v[180:183], 0
	v_mfma_f32_16x16x32_bf16 v[120:123], v[156:159], v[180:183], 0
	v_mfma_f32_16x16x32_bf16 v[112:115], v[148:151], v[188:191], 0
	v_mfma_f32_16x16x32_bf16 v[104:107], v[156:159], v[188:191], 0
	v_mfma_f32_16x16x32_bf16 v[96:99], v[148:151], v[206:209], 0
	v_mfma_f32_16x16x32_bf16 v[88:91], v[156:159], v[206:209], 0
	v_mfma_f32_16x16x32_bf16 v[80:83], v[148:151], v[214:217], 0
	v_mfma_f32_16x16x32_bf16 v[72:75], v[156:159], v[214:217], 0
	v_mfma_f32_16x16x32_bf16 v[128:131], v[152:155], v[184:187], v[128:131]
	v_mfma_f32_16x16x32_bf16 v[120:123], v[160:163], v[184:187], v[120:123]
	v_mfma_f32_16x16x32_bf16 v[112:115], v[152:155], v[192:195], v[112:115]
	v_mfma_f32_16x16x32_bf16 v[104:107], v[160:163], v[192:195], v[104:107]
	v_mfma_f32_16x16x32_bf16 v[96:99], v[152:155], v[210:213], v[96:99]
	v_mfma_f32_16x16x32_bf16 v[88:91], v[160:163], v[210:213], v[88:91]
	v_mfma_f32_16x16x32_bf16 v[80:83], v[152:155], v[218:221], v[80:83]
	v_mfma_f32_16x16x32_bf16 v[72:75], v[160:163], v[218:221], v[72:75]
	v_mfma_f32_16x16x32_bf16 v[124:127], v[164:167], v[180:183], 0
	v_mfma_f32_16x16x32_bf16 v[116:119], v[172:175], v[180:183], 0
	v_mfma_f32_16x16x32_bf16 v[108:111], v[164:167], v[188:191], 0
	v_mfma_f32_16x16x32_bf16 v[100:103], v[172:175], v[188:191], 0
	v_mfma_f32_16x16x32_bf16 v[92:95], v[164:167], v[206:209], 0
	v_mfma_f32_16x16x32_bf16 v[84:87], v[172:175], v[206:209], 0
	v_mfma_f32_16x16x32_bf16 v[76:79], v[164:167], v[214:217], 0
	v_mfma_f32_16x16x32_bf16 v[68:71], v[172:175], v[214:217], 0
	v_mfma_f32_16x16x32_bf16 v[124:127], v[168:171], v[184:187], v[124:127]
	v_mfma_f32_16x16x32_bf16 v[116:119], v[176:179], v[184:187], v[116:119]
	v_mfma_f32_16x16x32_bf16 v[108:111], v[168:171], v[192:195], v[108:111]
	v_mfma_f32_16x16x32_bf16 v[100:103], v[176:179], v[192:195], v[100:103]
	v_mfma_f32_16x16x32_bf16 v[92:95], v[168:171], v[210:213], v[92:95]
	v_mfma_f32_16x16x32_bf16 v[84:87], v[176:179], v[210:213], v[84:87]
	v_mfma_f32_16x16x32_bf16 v[76:79], v[168:171], v[218:221], v[76:79]
	v_mfma_f32_16x16x32_bf16 v[68:71], v[176:179], v[218:221], v[68:71]
	s_barrier
	s_add_i32 s63, s63, s36
	s_mov_b32 m0, s63
	ds_read_b128 v[180:183], v146 offset:16384
	ds_read_b128 v[184:187], v146 offset:17408
	ds_read_b128 v[188:191], v146 offset:18432
	ds_read_b128 v[192:195], v146 offset:19456
	ds_read_b128 v[206:209], v146 offset:20480
	ds_read_b128 v[210:213], v146 offset:21504
	ds_read_b128 v[214:217], v146 offset:22528
	ds_read_b128 v[218:221], v146 offset:23552
	global_load_lds_dwordx4 v2, s[30:31]
	s_add_i32 m0, s63, 0x2000
	s_add_u32 s64, s30, 0x40000
	s_addc_u32 s65, s31, 0
	s_add_i32 s63, s66, s36
	global_load_lds_dwordx4 v132, s[30:31]
	s_mov_b32 m0, s63
	global_load_lds_dwordx4 v2, s[64:65]
	s_add_i32 m0, s63, 0x2000
	s_nop 0
	global_load_lds_dwordx4 v132, s[64:65]
	s_mov_b32 m0, s45
	s_nop 0
	global_load_lds_dwordx4 v136, s[34:35]
	s_mov_b32 m0, s46
	s_nop 0
	global_load_lds_dwordx4 v134, s[34:35]
	s_add_i32 s55, s55, 1
	s_mul_i32 s23, s55, s84
	s_mul_hi_u32 s25, s55, s83
	s_add_i32 s25, s25, s23
	s_mul_i32 s23, s55, s83
	s_add_u32 s100, s23, s2
	s_addc_u32 s101, s25, s93
	v_cmp_gt_i64_e32 vcc, s[100:101], v[202:203]
	v_cmp_lt_i64_e64 s[38:39], s[100:101], v[200:201]
	s_cbranch_vccnz .Lm7_nonext
	s_and_b32 s25, s100, 7
	s_lshr_b32 s23, s100, 3
	s_mul_i32 s101, s25, 0xb3
	s_sub_i32 s100, s25, 6
	s_max_i32 s100, s100, 0
	s_sub_i32 s101, s101, s100
	s_add_i32 s23, s23, s101
	s_mul_hi_i32 s25, s23, 0x2e8ba2e9
	s_ashr_i32 s25, s25, 3
	s_mul_i32 s101, s25, 44
	s_sub_i32 s23, s23, s101
	s_lshl_b32 s25, s25, 1
	s_sub_i32 s101, 0x41, s25
	s_min_i32 s101, s101, 2
	s_sub_i32 s101, s101, 1
	s_lshr_b32 s22, s23, s101
	s_and_b32 s23, s23, s101
	s_add_i32 s24, s25, s23
.Lm7_nonext:
	s_lshl_b32 s100, s24, 19
	s_add_u32 s26, s37, s100
	s_addc_u32 s27, s44, 0
	s_and_b64 s[100:101], s[38:39], exec
	s_cselect_b32 s25, s27, s29
	s_cselect_b32 s58, s26, s28
	s_lshl_b32 s100, s22, 19
	s_add_u32 s42, s40, s100
	s_addc_u32 s43, s41, 0
	s_and_b64 s[100:101], s[38:39], exec
	s_cselect_b32 s23, s43, s61
	s_cselect_b32 s59, s42, s60
	s_waitcnt vmcnt(8)
	s_waitcnt lgkmcnt(0)
	s_barrier
	s_waitcnt lgkmcnt(0)
	v_mfma_f32_16x16x32_bf16 v[64:67], v[148:151], v[180:183], 0
	v_mfma_f32_16x16x32_bf16 v[56:59], v[156:159], v[180:183], 0
	v_mfma_f32_16x16x32_bf16 v[48:51], v[148:151], v[188:191], 0
	v_mfma_f32_16x16x32_bf16 v[40:43], v[156:159], v[188:191], 0
	v_mfma_f32_16x16x32_bf16 v[32:35], v[148:151], v[206:209], 0
	v_mfma_f32_16x16x32_bf16 v[24:27], v[156:159], v[206:209], 0
	v_mfma_f32_16x16x32_bf16 v[16:19], v[148:151], v[214:217], 0
	v_mfma_f32_16x16x32_bf16 v[8:11], v[156:159], v[214:217], 0
	v_mfma_f32_16x16x32_bf16 v[64:67], v[152:155], v[184:187], v[64:67]
	v_mfma_f32_16x16x32_bf16 v[56:59], v[160:163], v[184:187], v[56:59]
	v_mfma_f32_16x16x32_bf16 v[48:51], v[152:155], v[192:195], v[48:51]
	v_mfma_f32_16x16x32_bf16 v[40:43], v[160:163], v[192:195], v[40:43]
	v_mfma_f32_16x16x32_bf16 v[32:35], v[152:155], v[210:213], v[32:35]
	v_mfma_f32_16x16x32_bf16 v[24:27], v[160:163], v[210:213], v[24:27]
	v_mfma_f32_16x16x32_bf16 v[16:19], v[152:155], v[218:221], v[16:19]
	v_mfma_f32_16x16x32_bf16 v[8:11], v[160:163], v[218:221], v[8:11]
	v_mfma_f32_16x16x32_bf16 v[60:63], v[164:167], v[180:183], 0
	v_mfma_f32_16x16x32_bf16 v[52:55], v[172:175], v[180:183], 0
	v_mfma_f32_16x16x32_bf16 v[44:47], v[164:167], v[188:191], 0
	v_mfma_f32_16x16x32_bf16 v[36:39], v[172:175], v[188:191], 0
	v_mfma_f32_16x16x32_bf16 v[28:31], v[164:167], v[206:209], 0
	v_mfma_f32_16x16x32_bf16 v[20:23], v[172:175], v[206:209], 0
	v_mfma_f32_16x16x32_bf16 v[12:15], v[164:167], v[214:217], 0
	v_mfma_f32_16x16x32_bf16 v[4:7], v[172:175], v[214:217], 0
	v_mfma_f32_16x16x32_bf16 v[60:63], v[168:171], v[184:187], v[60:63]
	v_mfma_f32_16x16x32_bf16 v[52:55], v[176:179], v[184:187], v[52:55]
	v_mfma_f32_16x16x32_bf16 v[44:47], v[168:171], v[192:195], v[44:47]
	v_mfma_f32_16x16x32_bf16 v[36:39], v[176:179], v[192:195], v[36:39]
	v_mfma_f32_16x16x32_bf16 v[28:31], v[168:171], v[210:213], v[28:31]
	v_mfma_f32_16x16x32_bf16 v[20:23], v[176:179], v[210:213], v[20:23]
	v_mfma_f32_16x16x32_bf16 v[12:15], v[168:171], v[218:221], v[12:15]
	v_mfma_f32_16x16x32_bf16 v[4:7], v[176:179], v[218:221], v[4:7]
	s_barrier
	s_add_i32 s63, 0, 0x18000
	v_add_u32_e32 v147, s63, v145
	s_add_i32 s64, 0, 0x1c000
	ds_read_b128 v[148:151], v147
	ds_read_b128 v[152:155], v147 offset:1024
	ds_read_b128 v[156:159], v147 offset:2048
	ds_read_b128 v[160:163], v147 offset:3072
	v_add_u32_e32 v147, s64, v145
	ds_read_b128 v[164:167], v147
	ds_read_b128 v[168:171], v147 offset:1024
	ds_read_b128 v[172:175], v147 offset:2048
	ds_read_b128 v[176:179], v147 offset:3072
	s_add_u32 s100, s34, 0x80
	s_addc_u32 s101, s35, 0
	s_add_u32 s34, s34, 0x40000
	s_addc_u32 s35, s35, 0
	s_mov_b32 m0, s47
	ds_read_b128 v[180:183], v146 offset:32768
	ds_read_b128 v[184:187], v146 offset:33792
	ds_read_b128 v[188:191], v146 offset:34816
	ds_read_b128 v[192:195], v146 offset:35840
	ds_read_b128 v[206:209], v146 offset:36864
	ds_read_b128 v[210:213], v146 offset:37888
	ds_read_b128 v[214:217], v146 offset:38912
	ds_read_b128 v[218:221], v146 offset:39936
	global_load_lds_dwordx4 v136, s[34:35]
	s_mov_b32 m0, s48
	s_nop 0
	global_load_lds_dwordx4 v134, s[34:35]
	s_waitcnt vmcnt(8)
	s_waitcnt lgkmcnt(0)
	s_barrier
	s_waitcnt lgkmcnt(0)
	v_mfma_f32_16x16x32_bf16 v[128:131], v[148:151], v[180:183], v[128:131]
	v_mfma_f32_16x16x32_bf16 v[120:123], v[156:159], v[180:183], v[120:123]
	v_mfma_f32_16x16x32_bf16 v[112:115], v[148:151], v[188:191], v[112:115]
	v_mfma_f32_16x16x32_bf16 v[104:107], v[156:159], v[188:191], v[104:107]
	v_mfma_f32_16x16x32_bf16 v[96:99], v[148:151], v[206:209], v[96:99]
	v_mfma_f32_16x16x32_bf16 v[88:91], v[156:159], v[206:209], v[88:91]
	v_mfma_f32_16x16x32_bf16 v[80:83], v[148:151], v[214:217], v[80:83]
	v_mfma_f32_16x16x32_bf16 v[72:75], v[156:159], v[214:217], v[72:75]
	v_mfma_f32_16x16x32_bf16 v[128:131], v[152:155], v[184:187], v[128:131]
	v_mfma_f32_16x16x32_bf16 v[120:123], v[160:163], v[184:187], v[120:123]
	v_mfma_f32_16x16x32_bf16 v[112:115], v[152:155], v[192:195], v[112:115]
	v_mfma_f32_16x16x32_bf16 v[104:107], v[160:163], v[192:195], v[104:107]
	v_mfma_f32_16x16x32_bf16 v[96:99], v[152:155], v[210:213], v[96:99]
	v_mfma_f32_16x16x32_bf16 v[88:91], v[160:163], v[210:213], v[88:91]
	v_mfma_f32_16x16x32_bf16 v[80:83], v[152:155], v[218:221], v[80:83]
	v_mfma_f32_16x16x32_bf16 v[72:75], v[160:163], v[218:221], v[72:75]
	v_mfma_f32_16x16x32_bf16 v[124:127], v[164:167], v[180:183], v[124:127]
	v_mfma_f32_16x16x32_bf16 v[116:119], v[172:175], v[180:183], v[116:119]
	v_mfma_f32_16x16x32_bf16 v[108:111], v[164:167], v[188:191], v[108:111]
	v_mfma_f32_16x16x32_bf16 v[100:103], v[172:175], v[188:191], v[100:103]
	v_mfma_f32_16x16x32_bf16 v[92:95], v[164:167], v[206:209], v[92:95]
	v_mfma_f32_16x16x32_bf16 v[84:87], v[172:175], v[206:209], v[84:87]
	v_mfma_f32_16x16x32_bf16 v[76:79], v[164:167], v[214:217], v[76:79]
	v_mfma_f32_16x16x32_bf16 v[68:71], v[172:175], v[214:217], v[68:71]
	v_mfma_f32_16x16x32_bf16 v[124:127], v[168:171], v[184:187], v[124:127]
	v_mfma_f32_16x16x32_bf16 v[116:119], v[176:179], v[184:187], v[116:119]
	v_mfma_f32_16x16x32_bf16 v[108:111], v[168:171], v[192:195], v[108:111]
	v_mfma_f32_16x16x32_bf16 v[100:103], v[176:179], v[192:195], v[100:103]
	v_mfma_f32_16x16x32_bf16 v[92:95], v[168:171], v[210:213], v[92:95]
	v_mfma_f32_16x16x32_bf16 v[84:87], v[176:179], v[210:213], v[84:87]
	v_mfma_f32_16x16x32_bf16 v[76:79], v[168:171], v[218:221], v[76:79]
	v_mfma_f32_16x16x32_bf16 v[68:71], v[176:179], v[218:221], v[68:71]
	s_barrier
	s_add_i32 s34, s63, s36
	s_mov_b32 m0, s34
	ds_read_b128 v[180:183], v146 offset:49152
	ds_read_b128 v[184:187], v146 offset:50176
	ds_read_b128 v[188:191], v146 offset:51200
	ds_read_b128 v[192:195], v146 offset:52224
	ds_read_b128 v[206:209], v146 offset:53248
	ds_read_b128 v[210:213], v146 offset:54272
	ds_read_b128 v[214:217], v146 offset:55296
	ds_read_b128 v[218:221], v146 offset:56320
	s_add_u32 s30, s30, 0x80
	s_addc_u32 s31, s31, 0
	global_load_lds_dwordx4 v2, s[30:31]
	s_add_i32 m0, s34, 0x2000
	s_add_i32 s34, s64, s36
	global_load_lds_dwordx4 v132, s[30:31]
	s_add_u32 s30, s30, 0x40000
	s_addc_u32 s31, s31, 0
	s_mov_b32 m0, s34
	s_nop 0
	global_load_lds_dwordx4 v2, s[30:31]
	s_add_i32 m0, s34, 0x2000
	s_nop 0
	global_load_lds_dwordx4 v132, s[30:31]
	s_mov_b32 m0, s51
	s_nop 0
	global_load_lds_dwordx4 v136, s[100:101]
	s_mov_b32 m0, s52
	s_nop 0
	global_load_lds_dwordx4 v134, s[100:101]
	s_waitcnt vmcnt(8)
	s_waitcnt lgkmcnt(0)
	s_barrier
	s_waitcnt lgkmcnt(0)
	v_mfma_f32_16x16x32_bf16 v[64:67], v[148:151], v[180:183], v[64:67]
	v_mfma_f32_16x16x32_bf16 v[56:59], v[156:159], v[180:183], v[56:59]
	v_mfma_f32_16x16x32_bf16 v[48:51], v[148:151], v[188:191], v[48:51]
	v_mfma_f32_16x16x32_bf16 v[40:43], v[156:159], v[188:191], v[40:43]
	v_mfma_f32_16x16x32_bf16 v[32:35], v[148:151], v[206:209], v[32:35]
	v_mfma_f32_16x16x32_bf16 v[24:27], v[156:159], v[206:209], v[24:27]
	v_mfma_f32_16x16x32_bf16 v[16:19], v[148:151], v[214:217], v[16:19]
	v_mfma_f32_16x16x32_bf16 v[8:11], v[156:159], v[214:217], v[8:11]
	v_mfma_f32_16x16x32_bf16 v[64:67], v[152:155], v[184:187], v[64:67]
	v_mfma_f32_16x16x32_bf16 v[56:59], v[160:163], v[184:187], v[56:59]
	v_mfma_f32_16x16x32_bf16 v[48:51], v[152:155], v[192:195], v[48:51]
	v_mfma_f32_16x16x32_bf16 v[40:43], v[160:163], v[192:195], v[40:43]
	v_mfma_f32_16x16x32_bf16 v[32:35], v[152:155], v[210:213], v[32:35]
	v_mfma_f32_16x16x32_bf16 v[24:27], v[160:163], v[210:213], v[24:27]
	v_mfma_f32_16x16x32_bf16 v[16:19], v[152:155], v[218:221], v[16:19]
	v_mfma_f32_16x16x32_bf16 v[8:11], v[160:163], v[218:221], v[8:11]
	v_mfma_f32_16x16x32_bf16 v[60:63], v[164:167], v[180:183], v[60:63]
	v_mfma_f32_16x16x32_bf16 v[52:55], v[172:175], v[180:183], v[52:55]
	v_mfma_f32_16x16x32_bf16 v[44:47], v[164:167], v[188:191], v[44:47]
	v_mfma_f32_16x16x32_bf16 v[36:39], v[172:175], v[188:191], v[36:39]
	v_mfma_f32_16x16x32_bf16 v[28:31], v[164:167], v[206:209], v[28:31]
	v_mfma_f32_16x16x32_bf16 v[20:23], v[172:175], v[206:209], v[20:23]
	v_mfma_f32_16x16x32_bf16 v[12:15], v[164:167], v[214:217], v[12:15]
	v_mfma_f32_16x16x32_bf16 v[4:7], v[172:175], v[214:217], v[4:7]
	v_mfma_f32_16x16x32_bf16 v[60:63], v[168:171], v[184:187], v[60:63]
	v_mfma_f32_16x16x32_bf16 v[52:55], v[176:179], v[184:187], v[52:55]
	v_mfma_f32_16x16x32_bf16 v[44:47], v[168:171], v[192:195], v[44:47]
	v_mfma_f32_16x16x32_bf16 v[36:39], v[176:179], v[192:195], v[36:39]
	v_mfma_f32_16x16x32_bf16 v[28:31], v[168:171], v[210:213], v[28:31]
	v_mfma_f32_16x16x32_bf16 v[20:23], v[176:179], v[210:213], v[20:23]
	v_mfma_f32_16x16x32_bf16 v[12:15], v[168:171], v[218:221], v[12:15]
	v_mfma_f32_16x16x32_bf16 v[4:7], v[176:179], v[218:221], v[4:7]
	s_barrier
	s_add_i32 s62, s62, 2
	s_add_u32 s28, s28, 0x100
	s_addc_u32 s29, s29, 0
	s_add_u32 s60, s60, 0x100
	s_addc_u32 s61, s61, 0
	s_cmp_gt_u32 s62, 13
.LBB0_316:
	s_add_u32 s30, s28, 0xfffc0080
	s_addc_u32 s31, s29, -1
	s_add_i32 s63, 0, 0x10000
	s_cmp_eq_u32 s62, 12
	s_cselect_b32 s35, s25, s31
	s_cselect_b32 s34, s58, s30
	v_add_u32_e32 v142, s63, v145
	s_cselect_b32 s31, s23, s61
	s_cselect_b32 s30, s59, s60
	s_add_i32 s66, 0, 0x14000
	ds_read_b128 v[148:151], v142
	ds_read_b128 v[152:155], v142 offset:1024
	ds_read_b128 v[156:159], v142 offset:2048
	ds_read_b128 v[160:163], v142 offset:3072
	v_add_u32_e32 v142, s66, v145
	ds_read_b128 v[164:167], v142
	ds_read_b128 v[168:171], v142 offset:1024
	ds_read_b128 v[172:175], v142 offset:2048
	ds_read_b128 v[176:179], v142 offset:3072
	s_add_i32 m0, s45, 0xc000
	ds_read_b128 v[180:183], v146
	ds_read_b128 v[184:187], v146 offset:1024
	ds_read_b128 v[188:191], v146 offset:2048
	ds_read_b128 v[192:195], v146 offset:3072
	ds_read_b128 v[206:209], v146 offset:4096
	ds_read_b128 v[210:213], v146 offset:5120
	ds_read_b128 v[214:217], v146 offset:6144
	ds_read_b128 v[218:221], v146 offset:7168
	global_load_lds_dwordx4 v138, s[28:29]
	s_add_i32 m0, s45, 0xe000
	s_nop 0
	global_load_lds_dwordx4 v140, s[28:29]
	s_waitcnt vmcnt(8)
	s_waitcnt lgkmcnt(0)
	s_barrier
	s_waitcnt lgkmcnt(0)
	v_mfma_f32_16x16x32_bf16 v[128:131], v[148:151], v[180:183], v[128:131]
	v_mfma_f32_16x16x32_bf16 v[120:123], v[156:159], v[180:183], v[120:123]
	v_mfma_f32_16x16x32_bf16 v[112:115], v[148:151], v[188:191], v[112:115]
	v_mfma_f32_16x16x32_bf16 v[104:107], v[156:159], v[188:191], v[104:107]
	v_mfma_f32_16x16x32_bf16 v[96:99], v[148:151], v[206:209], v[96:99]
	v_mfma_f32_16x16x32_bf16 v[88:91], v[156:159], v[206:209], v[88:91]
	v_mfma_f32_16x16x32_bf16 v[80:83], v[148:151], v[214:217], v[80:83]
	v_mfma_f32_16x16x32_bf16 v[72:75], v[156:159], v[214:217], v[72:75]
	v_mfma_f32_16x16x32_bf16 v[128:131], v[152:155], v[184:187], v[128:131]
	v_mfma_f32_16x16x32_bf16 v[120:123], v[160:163], v[184:187], v[120:123]
	v_mfma_f32_16x16x32_bf16 v[112:115], v[152:155], v[192:195], v[112:115]
	v_mfma_f32_16x16x32_bf16 v[104:107], v[160:163], v[192:195], v[104:107]
	v_mfma_f32_16x16x32_bf16 v[96:99], v[152:155], v[210:213], v[96:99]
	v_mfma_f32_16x16x32_bf16 v[88:91], v[160:163], v[210:213], v[88:91]
	v_mfma_f32_16x16x32_bf16 v[80:83], v[152:155], v[218:221], v[80:83]
	v_mfma_f32_16x16x32_bf16 v[72:75], v[160:163], v[218:221], v[72:75]
	v_mfma_f32_16x16x32_bf16 v[124:127], v[164:167], v[180:183], v[124:127]
	v_mfma_f32_16x16x32_bf16 v[116:119], v[172:175], v[180:183], v[116:119]
	v_mfma_f32_16x16x32_bf16 v[108:111], v[164:167], v[188:191], v[108:111]
	v_mfma_f32_16x16x32_bf16 v[100:103], v[172:175], v[188:191], v[100:103]
	v_mfma_f32_16x16x32_bf16 v[92:95], v[164:167], v[206:209], v[92:95]
	v_mfma_f32_16x16x32_bf16 v[84:87], v[172:175], v[206:209], v[84:87]
	v_mfma_f32_16x16x32_bf16 v[76:79], v[164:167], v[214:217], v[76:79]
	v_mfma_f32_16x16x32_bf16 v[68:71], v[172:175], v[214:217], v[68:71]
	v_mfma_f32_16x16x32_bf16 v[124:127], v[168:171], v[184:187], v[124:127]
	v_mfma_f32_16x16x32_bf16 v[116:119], v[176:179], v[184:187], v[116:119]
	v_mfma_f32_16x16x32_bf16 v[108:111], v[168:171], v[192:195], v[108:111]
	v_mfma_f32_16x16x32_bf16 v[100:103], v[176:179], v[192:195], v[100:103]
	v_mfma_f32_16x16x32_bf16 v[92:95], v[168:171], v[210:213], v[92:95]
	v_mfma_f32_16x16x32_bf16 v[84:87], v[176:179], v[210:213], v[84:87]
	v_mfma_f32_16x16x32_bf16 v[76:79], v[168:171], v[218:221], v[76:79]
	v_mfma_f32_16x16x32_bf16 v[68:71], v[176:179], v[218:221], v[68:71]
	s_barrier
	s_add_i32 s63, s63, s36
	s_mov_b32 m0, s63
	ds_read_b128 v[180:183], v146 offset:16384
	ds_read_b128 v[184:187], v146 offset:17408
	ds_read_b128 v[188:191], v146 offset:18432
	ds_read_b128 v[192:195], v146 offset:19456
	ds_read_b128 v[206:209], v146 offset:20480
	ds_read_b128 v[210:213], v146 offset:21504
	ds_read_b128 v[214:217], v146 offset:22528
	ds_read_b128 v[218:221], v146 offset:23552
	global_load_lds_dwordx4 v2, s[30:31]
	s_add_i32 m0, s63, 0x2000
	s_add_u32 s64, s30, 0x40000
	s_addc_u32 s65, s31, 0
	s_add_i32 s63, s66, s36
	global_load_lds_dwordx4 v132, s[30:31]
	s_mov_b32 m0, s63
	global_load_lds_dwordx4 v2, s[64:65]
	s_add_i32 m0, s63, 0x2000
	s_nop 0
	global_load_lds_dwordx4 v132, s[64:65]
	s_mov_b32 m0, s45
	s_nop 0
	global_load_lds_dwordx4 v136, s[34:35]
	s_mov_b32 m0, s46
	s_nop 0
	global_load_lds_dwordx4 v134, s[34:35]
	s_waitcnt vmcnt(8)
	s_waitcnt lgkmcnt(0)
	s_barrier
	s_waitcnt lgkmcnt(0)
	v_mfma_f32_16x16x32_bf16 v[64:67], v[148:151], v[180:183], v[64:67]
	v_mfma_f32_16x16x32_bf16 v[56:59], v[156:159], v[180:183], v[56:59]
	v_mfma_f32_16x16x32_bf16 v[48:51], v[148:151], v[188:191], v[48:51]
	v_mfma_f32_16x16x32_bf16 v[40:43], v[156:159], v[188:191], v[40:43]
	v_mfma_f32_16x16x32_bf16 v[32:35], v[148:151], v[206:209], v[32:35]
	v_mfma_f32_16x16x32_bf16 v[24:27], v[156:159], v[206:209], v[24:27]
	v_mfma_f32_16x16x32_bf16 v[16:19], v[148:151], v[214:217], v[16:19]
	v_mfma_f32_16x16x32_bf16 v[8:11], v[156:159], v[214:217], v[8:11]
	v_mfma_f32_16x16x32_bf16 v[64:67], v[152:155], v[184:187], v[64:67]
	v_mfma_f32_16x16x32_bf16 v[56:59], v[160:163], v[184:187], v[56:59]
	v_mfma_f32_16x16x32_bf16 v[48:51], v[152:155], v[192:195], v[48:51]
	v_mfma_f32_16x16x32_bf16 v[40:43], v[160:163], v[192:195], v[40:43]
	v_mfma_f32_16x16x32_bf16 v[32:35], v[152:155], v[210:213], v[32:35]
	v_mfma_f32_16x16x32_bf16 v[24:27], v[160:163], v[210:213], v[24:27]
	v_mfma_f32_16x16x32_bf16 v[16:19], v[152:155], v[218:221], v[16:19]
	v_mfma_f32_16x16x32_bf16 v[8:11], v[160:163], v[218:221], v[8:11]
	v_mfma_f32_16x16x32_bf16 v[60:63], v[164:167], v[180:183], v[60:63]
	v_mfma_f32_16x16x32_bf16 v[52:55], v[172:175], v[180:183], v[52:55]
	v_mfma_f32_16x16x32_bf16 v[44:47], v[164:167], v[188:191], v[44:47]
	v_mfma_f32_16x16x32_bf16 v[36:39], v[172:175], v[188:191], v[36:39]
	v_mfma_f32_16x16x32_bf16 v[28:31], v[164:167], v[206:209], v[28:31]
	v_mfma_f32_16x16x32_bf16 v[20:23], v[172:175], v[206:209], v[20:23]
	v_mfma_f32_16x16x32_bf16 v[12:15], v[164:167], v[214:217], v[12:15]
	v_mfma_f32_16x16x32_bf16 v[4:7], v[172:175], v[214:217], v[4:7]
	v_mfma_f32_16x16x32_bf16 v[60:63], v[168:171], v[184:187], v[60:63]
	v_mfma_f32_16x16x32_bf16 v[52:55], v[176:179], v[184:187], v[52:55]
	v_mfma_f32_16x16x32_bf16 v[44:47], v[168:171], v[192:195], v[44:47]
	v_mfma_f32_16x16x32_bf16 v[36:39], v[176:179], v[192:195], v[36:39]
	v_mfma_f32_16x16x32_bf16 v[28:31], v[168:171], v[210:213], v[28:31]
	v_mfma_f32_16x16x32_bf16 v[20:23], v[176:179], v[210:213], v[20:23]
	v_mfma_f32_16x16x32_bf16 v[12:15], v[168:171], v[218:221], v[12:15]
	v_mfma_f32_16x16x32_bf16 v[4:7], v[176:179], v[218:221], v[4:7]
	s_barrier
	s_add_i32 s63, 0, 0x18000
	v_add_u32_e32 v147, s63, v145
	s_add_i32 s64, 0, 0x1c000
	ds_read_b128 v[148:151], v147
	ds_read_b128 v[152:155], v147 offset:1024
	ds_read_b128 v[156:159], v147 offset:2048
	ds_read_b128 v[160:163], v147 offset:3072
	v_add_u32_e32 v147, s64, v145
	ds_read_b128 v[164:167], v147
	ds_read_b128 v[168:171], v147 offset:1024
	ds_read_b128 v[172:175], v147 offset:2048
	ds_read_b128 v[176:179], v147 offset:3072
	s_add_u32 s100, s34, 0x80
	s_addc_u32 s101, s35, 0
	s_add_u32 s34, s34, 0x40000
	s_addc_u32 s35, s35, 0
	s_mov_b32 m0, s47
	ds_read_b128 v[180:183], v146 offset:32768
	ds_read_b128 v[184:187], v146 offset:33792
	ds_read_b128 v[188:191], v146 offset:34816
	ds_read_b128 v[192:195], v146 offset:35840
	ds_read_b128 v[206:209], v146 offset:36864
	ds_read_b128 v[210:213], v146 offset:37888
	ds_read_b128 v[214:217], v146 offset:38912
	ds_read_b128 v[218:221], v146 offset:39936
	global_load_lds_dwordx4 v136, s[34:35]
	s_mov_b32 m0, s48
	s_nop 0
	global_load_lds_dwordx4 v134, s[34:35]
	s_waitcnt vmcnt(8)
	s_waitcnt lgkmcnt(0)
	s_barrier
	s_waitcnt lgkmcnt(0)
	v_mfma_f32_16x16x32_bf16 v[128:131], v[148:151], v[180:183], v[128:131]
	v_mfma_f32_16x16x32_bf16 v[120:123], v[156:159], v[180:183], v[120:123]
	v_mfma_f32_16x16x32_bf16 v[112:115], v[148:151], v[188:191], v[112:115]
	v_mfma_f32_16x16x32_bf16 v[104:107], v[156:159], v[188:191], v[104:107]
	v_mfma_f32_16x16x32_bf16 v[96:99], v[148:151], v[206:209], v[96:99]
	v_mfma_f32_16x16x32_bf16 v[88:91], v[156:159], v[206:209], v[88:91]
	v_mfma_f32_16x16x32_bf16 v[80:83], v[148:151], v[214:217], v[80:83]
	v_mfma_f32_16x16x32_bf16 v[72:75], v[156:159], v[214:217], v[72:75]
	v_mfma_f32_16x16x32_bf16 v[128:131], v[152:155], v[184:187], v[128:131]
	v_mfma_f32_16x16x32_bf16 v[120:123], v[160:163], v[184:187], v[120:123]
	v_mfma_f32_16x16x32_bf16 v[112:115], v[152:155], v[192:195], v[112:115]
	v_mfma_f32_16x16x32_bf16 v[104:107], v[160:163], v[192:195], v[104:107]
	v_mfma_f32_16x16x32_bf16 v[96:99], v[152:155], v[210:213], v[96:99]
	v_mfma_f32_16x16x32_bf16 v[88:91], v[160:163], v[210:213], v[88:91]
	v_mfma_f32_16x16x32_bf16 v[80:83], v[152:155], v[218:221], v[80:83]
	v_mfma_f32_16x16x32_bf16 v[72:75], v[160:163], v[218:221], v[72:75]
	v_mfma_f32_16x16x32_bf16 v[124:127], v[164:167], v[180:183], v[124:127]
	v_mfma_f32_16x16x32_bf16 v[116:119], v[172:175], v[180:183], v[116:119]
	v_mfma_f32_16x16x32_bf16 v[108:111], v[164:167], v[188:191], v[108:111]
	v_mfma_f32_16x16x32_bf16 v[100:103], v[172:175], v[188:191], v[100:103]
	v_mfma_f32_16x16x32_bf16 v[92:95], v[164:167], v[206:209], v[92:95]
	v_mfma_f32_16x16x32_bf16 v[84:87], v[172:175], v[206:209], v[84:87]
	v_mfma_f32_16x16x32_bf16 v[76:79], v[164:167], v[214:217], v[76:79]
	v_mfma_f32_16x16x32_bf16 v[68:71], v[172:175], v[214:217], v[68:71]
	v_mfma_f32_16x16x32_bf16 v[124:127], v[168:171], v[184:187], v[124:127]
	v_mfma_f32_16x16x32_bf16 v[116:119], v[176:179], v[184:187], v[116:119]
	v_mfma_f32_16x16x32_bf16 v[108:111], v[168:171], v[192:195], v[108:111]
	v_mfma_f32_16x16x32_bf16 v[100:103], v[176:179], v[192:195], v[100:103]
	v_mfma_f32_16x16x32_bf16 v[92:95], v[168:171], v[210:213], v[92:95]
	v_mfma_f32_16x16x32_bf16 v[84:87], v[176:179], v[210:213], v[84:87]
	v_mfma_f32_16x16x32_bf16 v[76:79], v[168:171], v[218:221], v[76:79]
	v_mfma_f32_16x16x32_bf16 v[68:71], v[176:179], v[218:221], v[68:71]
	s_barrier
	s_add_i32 s34, s63, s36
	s_mov_b32 m0, s34
	ds_read_b128 v[180:183], v146 offset:49152
	ds_read_b128 v[184:187], v146 offset:50176
	ds_read_b128 v[188:191], v146 offset:51200
	ds_read_b128 v[192:195], v146 offset:52224
	ds_read_b128 v[206:209], v146 offset:53248
	ds_read_b128 v[210:213], v146 offset:54272
	ds_read_b128 v[214:217], v146 offset:55296
	ds_read_b128 v[218:221], v146 offset:56320
	s_add_u32 s30, s30, 0x80
	s_addc_u32 s31, s31, 0
	global_load_lds_dwordx4 v2, s[30:31]
	s_add_i32 m0, s34, 0x2000
	s_add_i32 s34, s64, s36
	global_load_lds_dwordx4 v132, s[30:31]
	s_add_u32 s30, s30, 0x40000
	s_addc_u32 s31, s31, 0
	s_mov_b32 m0, s34
	s_nop 0
	global_load_lds_dwordx4 v2, s[30:31]
	s_add_i32 m0, s34, 0x2000
	s_nop 0
	global_load_lds_dwordx4 v132, s[30:31]
	s_mov_b32 m0, s51
	s_nop 0
	global_load_lds_dwordx4 v136, s[100:101]
	s_mov_b32 m0, s52
	s_nop 0
	global_load_lds_dwordx4 v134, s[100:101]
	s_waitcnt vmcnt(8)
	s_waitcnt lgkmcnt(0)
	s_barrier
	s_waitcnt lgkmcnt(0)
	v_mfma_f32_16x16x32_bf16 v[64:67], v[148:151], v[180:183], v[64:67]
	v_mfma_f32_16x16x32_bf16 v[56:59], v[156:159], v[180:183], v[56:59]
	v_mfma_f32_16x16x32_bf16 v[48:51], v[148:151], v[188:191], v[48:51]
	v_mfma_f32_16x16x32_bf16 v[40:43], v[156:159], v[188:191], v[40:43]
	v_mfma_f32_16x16x32_bf16 v[32:35], v[148:151], v[206:209], v[32:35]
	v_mfma_f32_16x16x32_bf16 v[24:27], v[156:159], v[206:209], v[24:27]
	v_mfma_f32_16x16x32_bf16 v[16:19], v[148:151], v[214:217], v[16:19]
	v_mfma_f32_16x16x32_bf16 v[8:11], v[156:159], v[214:217], v[8:11]
	v_mfma_f32_16x16x32_bf16 v[64:67], v[152:155], v[184:187], v[64:67]
	v_mfma_f32_16x16x32_bf16 v[56:59], v[160:163], v[184:187], v[56:59]
	v_mfma_f32_16x16x32_bf16 v[48:51], v[152:155], v[192:195], v[48:51]
	v_mfma_f32_16x16x32_bf16 v[40:43], v[160:163], v[192:195], v[40:43]
	v_mfma_f32_16x16x32_bf16 v[32:35], v[152:155], v[210:213], v[32:35]
	v_mfma_f32_16x16x32_bf16 v[24:27], v[160:163], v[210:213], v[24:27]
	v_mfma_f32_16x16x32_bf16 v[16:19], v[152:155], v[218:221], v[16:19]
	v_mfma_f32_16x16x32_bf16 v[8:11], v[160:163], v[218:221], v[8:11]
	v_mfma_f32_16x16x32_bf16 v[60:63], v[164:167], v[180:183], v[60:63]
	v_mfma_f32_16x16x32_bf16 v[52:55], v[172:175], v[180:183], v[52:55]
	v_mfma_f32_16x16x32_bf16 v[44:47], v[164:167], v[188:191], v[44:47]
	v_mfma_f32_16x16x32_bf16 v[36:39], v[172:175], v[188:191], v[36:39]
	v_mfma_f32_16x16x32_bf16 v[28:31], v[164:167], v[206:209], v[28:31]
	v_mfma_f32_16x16x32_bf16 v[20:23], v[172:175], v[206:209], v[20:23]
	v_mfma_f32_16x16x32_bf16 v[12:15], v[164:167], v[214:217], v[12:15]
	v_mfma_f32_16x16x32_bf16 v[4:7], v[172:175], v[214:217], v[4:7]
	v_mfma_f32_16x16x32_bf16 v[60:63], v[168:171], v[184:187], v[60:63]
	v_mfma_f32_16x16x32_bf16 v[52:55], v[176:179], v[184:187], v[52:55]
	v_mfma_f32_16x16x32_bf16 v[44:47], v[168:171], v[192:195], v[44:47]
	v_mfma_f32_16x16x32_bf16 v[36:39], v[176:179], v[192:195], v[36:39]
	v_mfma_f32_16x16x32_bf16 v[28:31], v[168:171], v[210:213], v[28:31]
	v_mfma_f32_16x16x32_bf16 v[20:23], v[176:179], v[210:213], v[20:23]
	v_mfma_f32_16x16x32_bf16 v[12:15], v[168:171], v[218:221], v[12:15]
	v_mfma_f32_16x16x32_bf16 v[4:7], v[176:179], v[218:221], v[4:7]
	s_barrier
	s_add_i32 s62, s62, 2
	s_add_u32 s28, s28, 0x100
	s_addc_u32 s29, s29, 0
	s_add_u32 s60, s60, 0x100
	s_addc_u32 s61, s61, 0
	s_cmp_gt_u32 s62, 13
	s_cbranch_scc0 .LBB0_316
	s_and_b64 vcc, exec, s[16:17]
	s_cbranch_vccz .LBB0_319
	v_lshl_add_u32 v147, v144, 4, v1
	v_add_u32_e32 v147, s53, v147
	v_lshlrev_b32_e32 v160, 6, v147
	v_add_u32_e32 v160, 0x20400, v160
	ds_read_b128 v[148:151], v160
	ds_read_b128 v[152:155], v160 offset:32
	ds_read_b128 v[156:159], v160 offset:16
	ds_read_b128 v[160:163], v160 offset:48
	s_mov_b32 s25, 0x800000
	v_lshl_add_u32 v147, v147, 2, v225
	s_waitcnt lgkmcnt(0)
	v_mov_b32_e32 v164, v148
	v_mov_b32_e32 v165, v152
	v_mov_b32_e32 v152, v149
	v_mov_b32_e32 v148, v150
	v_mov_b32_e32 v149, v154
	v_mov_b32_e32 v154, v151
	v_mov_b32_e32 v150, v156
	v_mov_b32_e32 v151, v160
	v_mov_b32_e32 v160, v157
	v_mov_b32_e32 v156, v158
	v_mov_b32_e32 v157, v162
	v_mov_b32_e32 v162, v159
	v_pk_add_f32 v[152:153], v[164:165], v[152:153]
	v_pk_add_f32 v[148:149], v[148:149], v[154:155]
	v_pk_add_f32 v[150:151], v[150:151], v[160:161]
	v_pk_add_f32 v[154:155], v[156:157], v[162:163]
	v_pk_add_f32 v[148:149], v[152:153], v[148:149]
	v_pk_add_f32 v[150:151], v[150:151], v[154:155]
	s_nop 0
	v_pk_add_f32 v[148:149], v[148:149], v[150:151]
	s_nop 0
	v_add_f32_e32 v148, v148, v149
	v_fmamk_f32 v148, v148, 0x3a800000, v223
	ds_write_b32 v147, v148 offset:17408
	v_mul_f32_e32 v149, 0x4b800000, v148
	v_cmp_gt_f32_e32 vcc, s25, v148
	s_nop 1
	v_cndmask_b32_e32 v148, v148, v149, vcc
	v_rsq_f32_e32 v148, v148
	s_nop 0
	v_mul_f32_e32 v149, 0x45800000, v148
	v_cndmask_b32_e32 v148, v148, v149, vcc
	ds_write_b32 v147, v148
	s_waitcnt lgkmcnt(0)
	s_barrier
